# rmsnorm row loop: last four butterfly steps of each row's sum of squares done with DPP moves instead of ds_bpermute, on top of v69
# speedup vs baseline: 1.0067x; 1.0009x over previous
; #define OPQV(x) asm volatile("" : "+v"(x))
; DEV void unpack8(const u32x4 v, float (&f)[8]) { f[0] = bflo(v.x); f[1] = bfhi(v.x); f[2] = bflo(v.y); f[3] = bfhi(v.y); f[4] = bflo(v.z); f[5] = bfhi(v.z); f[6] = bflo(v.w); f[7] = bfhi(v.w); }
; template <int RB>
; DEV void rmsnorm_rows(const float* srcf, const bf16_t* srcb, const float* gamma, bf16_t* H, bf16_t* cpy, float* outn, int row0, int lane) {
;     ...
;         for (int r = 0; r < RB; ++r)
; #pragma unroll
;             for (int hf = 0; hf < 2; ++hf) raw[r][hf] = *(const u32x4*)(srcb + (size_t)(row0 + r) * 1024 + hf * 512 + lane * 8);
; #pragma unroll
;         for (int r = 0; r < RB; ++r)
; #pragma unroll
;             for (int hf = 0; hf < 2; ++hf) { float t8[8]; unpack8(raw[r][hf], t8);
; #pragma unroll
;                 for (int j = 0; j < 8; ++j) v[r][hf * 8 + j] = t8[j]; }
;     }
;     f32x4 g0[2], g1[2];
; #pragma unroll
;     for (int hf = 0; hf < 2; ++hf) { g0[hf] = *(const f32x4*)(gamma + hf * 512 + lane * 8); g1[hf] = *(const f32x4*)(gamma + hf * 512 + lane * 8 + 4); }
; #pragma unroll
;     for (int r = 0; r < RB; ++r) {
;         float ss = 0.f;
; #pragma unroll
;         for (int j = 0; j < 16; ++j) ss += v[r][j] * v[r][j];
;         ss = wave_sum(ss);
;         const float rs = rsqrtf(ss * (1.f / 1024.f) + EPS_);
; DEV void phase_rmsnorm(const float* srcf, const bf16_t* srcb, const float* gamma, bf16_t* H, bf16_t* cpy, float* outn) {
;     int tid = threadIdx.x; OPQV(tid); const int lane = tid & 63, wave = tid >> 6;
;     for (int rq = blockIdx.x * 8 + wave; rq < T_ / 4; rq += gridDim.x * 8) rmsnorm_rows<4>(srcf, srcb, gamma, H, cpy, outn, rq * 4, lane);
.LBB0_52:
	v_ashrrev_i32_e32 v39, 31, v38
	v_lshlrev_b64 v[46:47], 11, v[38:39]
	v_lshl_add_u64 v[2:3], v[32:33], 0, v[46:47]
	v_add_u32_e32 v2, 1, v38
	v_ashrrev_i32_e32 v3, 31, v2
	v_lshlrev_b64 v[44:45], 11, v[2:3]
	v_lshl_add_u64 v[2:3], v[32:33], 0, v[44:45]
	v_add_u32_e32 v2, 2, v38
	v_ashrrev_i32_e32 v3, 31, v2
	v_lshlrev_b64 v[42:43], 11, v[2:3]
	v_lshl_add_u64 v[2:3], v[32:33], 0, v[42:43]
	v_add_u32_e32 v2, 3, v38
	v_ashrrev_i32_e32 v3, 31, v2
	v_lshlrev_b64 v[40:41], 11, v[2:3]
	v_lshl_add_u64 v[2:3], v[32:33], 0, v[40:41]
	s_nop 0
	v_lshl_add_u64 v[44:45], v[36:37], 0, v[44:45]
	v_add_u32_e32 v48, s4, v48
	v_add_u32_e32 v38, s5, v38
	v_mov_b64_e32 v[6:7], v[104:105]
	v_mov_b64_e32 v[8:9], v[106:107]
	v_mov_b64_e32 v[28:29], v[108:109]
	v_mov_b64_e32 v[30:31], v[110:111]
	v_mov_b64_e32 v[10:11], v[112:113]
	v_mov_b64_e32 v[12:13], v[114:115]
	v_mov_b64_e32 v[24:25], v[116:117]
	v_mov_b64_e32 v[26:27], v[118:119]
	v_mov_b64_e32 v[14:15], v[120:121]
	v_mov_b64_e32 v[16:17], v[122:123]
	v_mov_b64_e32 v[20:21], v[124:125]
	v_mov_b64_e32 v[22:23], v[126:127]
	v_mov_b64_e32 v[100:101], v[128:129]
	v_mov_b64_e32 v[102:103], v[130:131]
	v_mov_b64_e32 v[2:3], v[132:133]
	v_mov_b64_e32 v[4:5], v[134:135]
	v_lshlrev_b32_e32 v97, 16, v6
	v_and_b32_e32 v95, 0xffff0000, v6
	v_lshlrev_b32_e32 v93, 16, v7
	v_and_b32_e32 v91, 0xffff0000, v7
	v_lshlrev_b32_e32 v98, 16, v8
	v_and_b32_e32 v96, 0xffff0000, v8
	v_lshlrev_b32_e32 v94, 16, v9
	v_and_b32_e32 v92, 0xffff0000, v9
	v_lshlrev_b32_e32 v85, 16, v10
	v_and_b32_e32 v83, 0xffff0000, v10
	v_lshlrev_b32_e32 v81, 16, v11
	v_and_b32_e32 v79, 0xffff0000, v11
	v_lshlrev_b32_e32 v86, 16, v12
	v_and_b32_e32 v84, 0xffff0000, v12
	v_lshlrev_b32_e32 v82, 16, v13
	v_and_b32_e32 v80, 0xffff0000, v13
	v_lshlrev_b32_e32 v73, 16, v14
	v_and_b32_e32 v71, 0xffff0000, v14
	v_lshlrev_b32_e32 v69, 16, v15
	v_and_b32_e32 v67, 0xffff0000, v15
	v_lshlrev_b32_e32 v74, 16, v16
	v_and_b32_e32 v72, 0xffff0000, v16
	v_lshlrev_b32_e32 v70, 16, v17
	v_and_b32_e32 v68, 0xffff0000, v17
	v_lshlrev_b32_e32 v66, 16, v20
	v_and_b32_e32 v65, 0xffff0000, v20
	v_lshlrev_b32_e32 v64, 16, v21
	v_and_b32_e32 v63, 0xffff0000, v21
	global_load_dwordx4 v[14:17], v[34:35], off offset:16
	global_load_dwordx4 v[18:21], v[34:35], off
	global_load_dwordx4 v[6:9], v[34:35], off offset:2064
	global_load_dwordx4 v[10:13], v[34:35], off offset:2048
	v_subrev_u32_e32 v145, s5, v38
	v_cmp_ge_i32_e32 vcc, s58, v48
	s_nop 1
	v_cndmask_b32_e32 v144, v145, v38, vcc
	v_ashrrev_i32_e32 v137, 31, v144
	v_mov_b32_e32 v136, v144
	v_lshlrev_b64 v[136:137], 11, v[136:137]
	v_lshl_add_u64 v[136:137], v[32:33], 0, v[136:137]
	v_add_co_u32_e32 v138, vcc, 0x1000, v136
	s_nop 1
	v_addc_co_u32_e32 v139, vcc, 0, v137, vcc
	global_load_dwordx4 v[104:107], v[136:137], off
	global_load_dwordx4 v[108:111], v[136:137], off offset:1024
	global_load_dwordx4 v[112:115], v[136:137], off offset:2048
	global_load_dwordx4 v[116:119], v[136:137], off offset:3072
	global_load_dwordx4 v[120:123], v[138:139], off
	global_load_dwordx4 v[124:127], v[138:139], off offset:1024
	global_load_dwordx4 v[128:131], v[138:139], off offset:2048
	global_load_dwordx4 v[132:135], v[138:139], off offset:3072
	v_mul_f32_e32 v99, v97, v97
	v_fmac_f32_e32 v99, v95, v95
	v_fmac_f32_e32 v99, v93, v93
	v_fmac_f32_e32 v99, v91, v91
	v_fmac_f32_e32 v99, v98, v98
	v_fmac_f32_e32 v99, v96, v96
	v_fmac_f32_e32 v99, v94, v94
	v_lshlrev_b32_e32 v90, 16, v28
	v_fmac_f32_e32 v99, v92, v92
	v_and_b32_e32 v89, 0xffff0000, v28
	v_fmac_f32_e32 v99, v90, v90
	v_lshlrev_b32_e32 v88, 16, v29
	v_fmac_f32_e32 v99, v89, v89
	v_and_b32_e32 v87, 0xffff0000, v29
	s_waitcnt vmcnt(12)
	v_lshlrev_b32_e32 v39, 16, v2
	v_and_b32_e32 v29, 0xffff0000, v2
	v_lshlrev_b32_e32 v28, 16, v3
	v_and_b32_e32 v0, 0xffff0000, v3
	v_fmac_f32_e32 v99, v88, v88
	v_and_b32_e32 v2, 0xffff0000, v30
	v_lshlrev_b32_e32 v3, 16, v30
	v_lshlrev_b32_e32 v78, 16, v24
	v_and_b32_e32 v77, 0xffff0000, v24
	v_lshlrev_b32_e32 v76, 16, v25
	v_and_b32_e32 v75, 0xffff0000, v25
	v_fmac_f32_e32 v99, v87, v87
	v_pk_mul_f32 v[24:25], v[2:3], v[2:3]
	v_lshlrev_b32_e32 v61, 16, v100
	v_add_f32_e32 v25, v25, v99
	v_add_f32_e32 v99, v24, v25
	v_and_b32_e32 v24, 0xffff0000, v31
	v_lshlrev_b32_e32 v25, 16, v31
	v_pk_mul_f32 v[30:31], v[24:25], v[24:25]
	v_and_b32_e32 v59, 0xffff0000, v100
	v_add_f32_e32 v31, v31, v99
	v_add_f32_e32 v30, v30, v31
	ds_bpermute_b32 v31, v49, v30
	v_lshlrev_b32_e32 v57, 16, v101
	v_and_b32_e32 v55, 0xffff0000, v101
	v_lshlrev_b32_e32 v62, 16, v102
	v_and_b32_e32 v60, 0xffff0000, v102
	s_waitcnt lgkmcnt(0)
	v_add_f32_e32 v30, v30, v31
	ds_bpermute_b32 v31, v50, v30
	v_lshlrev_b32_e32 v58, 16, v103
	v_and_b32_e32 v56, 0xffff0000, v103
	s_waitcnt lgkmcnt(0)
	v_add_f32_e32 v30, v30, v31
	s_nop 1
	v_mov_b32_dpp v31, v30 row_mirror row_mask:0xf bank_mask:0xf
	s_waitcnt lgkmcnt(0)
	v_add_f32_e32 v30, v30, v31
	s_nop 1
	v_mov_b32_dpp v31, v30 row_half_mirror row_mask:0xf bank_mask:0xf
	s_waitcnt lgkmcnt(0)
	v_add_f32_e32 v30, v30, v31
	s_nop 1
	v_mov_b32_dpp v31, v30 quad_perm:[2,3,0,1] row_mask:0xf bank_mask:0xf
	s_waitcnt lgkmcnt(0)
	v_add_f32_e32 v30, v30, v31
	s_nop 1
	v_mov_b32_dpp v31, v30 quad_perm:[1,0,3,2] row_mask:0xf bank_mask:0xf
	s_waitcnt lgkmcnt(0)
	v_add_f32_e32 v30, v30, v31
	v_fmamk_f32 v30, v30, 0x3a800000, v211
	v_cmp_gt_f32_e32 vcc, s33, v30
	v_mul_f32_e32 v31, 0x4b800000, v30
	s_nop 0
	v_cndmask_b32_e32 v30, v30, v31, vcc
	v_rsq_f32_e32 v30, v30
	s_nop 0
	v_mul_f32_e32 v31, 0x45800000, v30
	v_cndmask_b32_e32 v99, v30, v31, vcc
	v_mul_f32_e32 v30, v99, v97
	v_mul_f32_e32 v31, v99, v98
	v_mul_f32_e32 v93, v99, v93
	s_waitcnt vmcnt(10)
; DEV u32x4 pack8(const float (&f)[8]) { u32x4 w; w.x = cvt_pk_bf16(f[0], f[1]); w.y = cvt_pk_bf16(f[2], f[3]); w.z = cvt_pk_bf16(f[4], f[5]); w.w = cvt_pk_bf16(f[6], f[7]); return w; }
; DEV float wave_sum(float v) {
; #pragma unroll
;     for (int o = 32; o >= 1; o >>= 1) v += __shfl_xor(v, o);
;     return v;
; }
; template <int RB>
; DEV void rmsnorm_rows(const float* srcf, const bf16_t* srcb, const float* gamma, bf16_t* H, bf16_t* cpy, float* outn, int row0, int lane) {
;     ...
;     for (int r = 0; r < RB; ++r) {
;         float ss = 0.f;
; #pragma unroll
;         for (int j = 0; j < 16; ++j) ss += v[r][j] * v[r][j];
;         ss = wave_sum(ss);
;         const float rs = rsqrtf(ss * (1.f / 1024.f) + EPS_);
;         const int row = row0 + r;
; #pragma unroll
;         for (int hf = 0; hf < 2; ++hf) { const int c = hf * 512 + lane * 8;
;             float y[8], x8[8];
; #pragma unroll
;             for (int j = 0; j < 4; ++j) { y[j] = v[r][hf * 8 + j] * rs * g0[hf][j]; y[4 + j] = v[r][hf * 8 + 4 + j] * rs * g1[hf][j]; }
; #pragma unroll
;             for (int j = 0; j < 8; ++j) x8[j] = v[r][hf * 8 + j];
;             if (cpy) *(u32x4*)(cpy + (size_t)row * 1024 + c) = pack8(x8);
;             if (outn) { *(f32x4*)(outn + (size_t)row * 1024 + c) = (f32x4){y[0], y[1], y[2], y[3]}; *(f32x4*)(outn + (size_t)row * 1024 + c + 4) = (f32x4){y[4], y[5], y[6], y[7]}; }
;             if (H) *(u32x4*)(H + (size_t)row * 1024 + c) = pack8(y); }
	v_mul_f32_e32 v30, v18, v30
	v_mul_f32_e32 v31, v14, v31
	v_mul_f32_e32 v95, v99, v95
	v_mul_f32_e32 v96, v99, v96
	v_mul_f32_e32 v93, v20, v93
	v_mul_f32_e32 v94, v99, v94
	v_mul_f32_e32 v91, v99, v91
	v_mul_f32_e32 v92, v99, v92
	v_mul_f32_e32 v88, v99, v88
	v_mul_f32_e32 v95, v19, v95
	v_mul_f32_e32 v96, v15, v96
	v_mul_f32_e32 v97, v16, v94
	v_mul_f32_e32 v91, v21, v91
	v_mul_f32_e32 v98, v17, v92
	v_cvt_pk_bf16_f32 v92, v30, v95
	v_cvt_pk_bf16_f32 v93, v93, v91
	v_cvt_pk_bf16_f32 v94, v31, v96
	v_lshl_add_u64 v[30:31], v[36:37], 0, v[46:47]
	v_mul_f32_e32 v46, v99, v90
	v_mul_f32_e32 v3, v99, v3
	v_mul_f32_e32 v47, v99, v89
	v_mul_f32_e32 v2, v99, v2
	s_waitcnt vmcnt(8)
	v_mul_f32_e32 v89, v12, v88
	v_mul_f32_e32 v25, v99, v25
	v_mul_f32_e32 v87, v99, v87
	v_mul_f32_e32 v24, v99, v24
	v_cvt_pk_bf16_f32 v95, v97, v98
	global_store_dwordx4 v[30:31], v[92:95], off
	v_mul_f32_e32 v46, v10, v46
	v_mul_f32_e32 v3, v6, v3
	v_mul_f32_e32 v47, v11, v47
	v_mul_f32_e32 v2, v7, v2
	v_mul_f32_e32 v25, v8, v25
	v_mul_f32_e32 v87, v13, v87
	v_mul_f32_e32 v24, v9, v24
	v_cvt_pk_bf16_f32 v88, v46, v47
	v_cvt_pk_bf16_f32 v89, v89, v87
	v_cvt_pk_bf16_f32 v90, v3, v2
	v_cvt_pk_bf16_f32 v91, v25, v24
	global_store_dwordx4 v[30:31], v[88:91], off offset:1024
	v_mul_f32_e32 v30, v85, v85
	v_fmac_f32_e32 v30, v83, v83
	v_fmac_f32_e32 v30, v81, v81
	v_fmac_f32_e32 v30, v79, v79
	v_fmac_f32_e32 v30, v86, v86
	v_fmac_f32_e32 v30, v84, v84
	v_fmac_f32_e32 v30, v82, v82
	v_fmac_f32_e32 v30, v80, v80
	v_fmac_f32_e32 v30, v78, v78
	v_fmac_f32_e32 v30, v77, v77
	v_fmac_f32_e32 v30, v76, v76
	v_and_b32_e32 v2, 0xffff0000, v26
	v_lshlrev_b32_e32 v3, 16, v26
	v_fmac_f32_e32 v30, v75, v75
	v_pk_mul_f32 v[24:25], v[2:3], v[2:3]
	v_lshlrev_b32_e32 v31, 16, v27
	v_add_f32_e32 v25, v25, v30
	v_and_b32_e32 v30, 0xffff0000, v27
	v_add_f32_e32 v26, v24, v25
	v_pk_mul_f32 v[24:25], v[30:31], v[30:31]
	s_nop 0
	v_add_f32_e32 v25, v25, v26
	v_add_f32_e32 v24, v24, v25
	ds_bpermute_b32 v25, v49, v24
	s_waitcnt lgkmcnt(0)
	v_add_f32_e32 v24, v24, v25
	ds_bpermute_b32 v25, v50, v24
	s_waitcnt lgkmcnt(0)
	v_add_f32_e32 v24, v24, v25
	s_nop 1
	v_mov_b32_dpp v25, v24 row_mirror row_mask:0xf bank_mask:0xf
	s_waitcnt lgkmcnt(0)
	v_add_f32_e32 v24, v24, v25
	s_nop 1
	v_mov_b32_dpp v25, v24 row_half_mirror row_mask:0xf bank_mask:0xf
	s_waitcnt lgkmcnt(0)
	v_add_f32_e32 v24, v24, v25
	s_nop 1
	v_mov_b32_dpp v25, v24 quad_perm:[2,3,0,1] row_mask:0xf bank_mask:0xf
	s_waitcnt lgkmcnt(0)
	v_add_f32_e32 v24, v24, v25
	s_nop 1
	v_mov_b32_dpp v25, v24 quad_perm:[1,0,3,2] row_mask:0xf bank_mask:0xf
	s_waitcnt lgkmcnt(0)
	v_add_f32_e32 v24, v24, v25
	v_fmamk_f32 v24, v24, 0x3a800000, v211
	v_cmp_gt_f32_e32 vcc, s33, v24
	v_mul_f32_e32 v25, 0x4b800000, v24
	s_nop 0
	v_cndmask_b32_e32 v24, v24, v25, vcc
	v_rsq_f32_e32 v24, v24
	s_nop 0
	v_mul_f32_e32 v25, 0x45800000, v24
	v_cndmask_b32_e32 v46, v24, v25, vcc
	v_mul_f32_e32 v25, v46, v86
	v_mul_f32_e32 v24, v46, v85
	v_mul_f32_e32 v26, v14, v25
	v_mul_f32_e32 v25, v46, v83
	v_mul_f32_e32 v24, v18, v24
	v_mul_f32_e32 v25, v19, v25
	v_mul_f32_e32 v27, v46, v84
	v_mul_f32_e32 v47, v46, v81
	v_mul_f32_e32 v79, v46, v79
	v_mul_f32_e32 v27, v15, v27
	v_mul_f32_e32 v47, v20, v47
	v_mul_f32_e32 v81, v46, v82
	v_mul_f32_e32 v79, v21, v79
	v_mul_f32_e32 v80, v46, v80
	v_cvt_pk_bf16_f32 v24, v24, v25
	v_cvt_pk_bf16_f32 v25, v47, v79
	v_cvt_pk_bf16_f32 v26, v26, v27
	v_mul_f32_e32 v81, v16, v81
	v_mul_f32_e32 v80, v17, v80
	v_cvt_pk_bf16_f32 v27, v81, v80
	global_store_dwordx4 v[44:45], v[24:27], off
	v_mul_f32_e32 v3, v46, v3
	v_mul_f32_e32 v2, v46, v2
	v_mul_f32_e32 v24, v46, v78
	v_mul_f32_e32 v25, v46, v77
	v_mul_f32_e32 v26, v46, v76
	v_mul_f32_e32 v24, v10, v24
	v_mul_f32_e32 v25, v11, v25
	v_mul_f32_e32 v26, v12, v26
	v_mul_f32_e32 v27, v46, v31
	v_mul_f32_e32 v31, v46, v75
	v_mul_f32_e32 v3, v6, v3
	v_mul_f32_e32 v2, v7, v2
	v_mul_f32_e32 v27, v8, v27
	v_mul_f32_e32 v31, v13, v31
	v_mul_f32_e32 v30, v46, v30
	v_cvt_pk_bf16_f32 v24, v24, v25
	v_cvt_pk_bf16_f32 v25, v26, v31
	v_cvt_pk_bf16_f32 v26, v3, v2
	v_mul_f32_e32 v30, v9, v30
	v_cvt_pk_bf16_f32 v27, v27, v30
	global_store_dwordx4 v[44:45], v[24:27], off offset:1024
	v_and_b32_e32 v2, 0xffff0000, v22
	v_lshlrev_b32_e32 v3, 16, v22
	v_mul_f32_e32 v26, v73, v73
	v_fmac_f32_e32 v26, v71, v71
	v_fmac_f32_e32 v26, v69, v69
	v_fmac_f32_e32 v26, v67, v67
	v_fmac_f32_e32 v26, v74, v74
	v_fmac_f32_e32 v26, v72, v72
	v_fmac_f32_e32 v26, v70, v70
	v_fmac_f32_e32 v26, v68, v68
	v_fmac_f32_e32 v26, v66, v66
	v_fmac_f32_e32 v26, v65, v65
	v_fmac_f32_e32 v26, v64, v64
	v_fmac_f32_e32 v26, v63, v63
	v_pk_mul_f32 v[24:25], v[2:3], v[2:3]
	v_lshlrev_b32_e32 v27, 16, v23
	v_add_f32_e32 v22, v25, v26
	v_and_b32_e32 v26, 0xffff0000, v23
	v_add_f32_e32 v24, v24, v22
	v_pk_mul_f32 v[22:23], v[26:27], v[26:27]
	s_nop 0
	v_add_f32_e32 v23, v23, v24
	v_add_f32_e32 v22, v22, v23
	ds_bpermute_b32 v23, v49, v22
	s_waitcnt lgkmcnt(0)
	v_add_f32_e32 v22, v22, v23
	ds_bpermute_b32 v23, v50, v22
	s_waitcnt lgkmcnt(0)
	v_add_f32_e32 v22, v22, v23
	s_nop 1
	v_mov_b32_dpp v23, v22 row_mirror row_mask:0xf bank_mask:0xf
	s_waitcnt lgkmcnt(0)
; DEV u32x4 pack8(const float (&f)[8]) { u32x4 w; w.x = cvt_pk_bf16(f[0], f[1]); w.y = cvt_pk_bf16(f[2], f[3]); w.z = cvt_pk_bf16(f[4], f[5]); w.w = cvt_pk_bf16(f[6], f[7]); return w; }
; DEV float wave_sum(float v) {
; #pragma unroll
;     for (int o = 32; o >= 1; o >>= 1) v += __shfl_xor(v, o);
;     return v;
; }
; template <int RB>
; DEV void rmsnorm_rows(const float* srcf, const bf16_t* srcb, const float* gamma, bf16_t* H, bf16_t* cpy, float* outn, int row0, int lane) {
;     ...
;     for (int r = 0; r < RB; ++r) {
;         float ss = 0.f;
; #pragma unroll
;         for (int j = 0; j < 16; ++j) ss += v[r][j] * v[r][j];
;         ss = wave_sum(ss);
;         const float rs = rsqrtf(ss * (1.f / 1024.f) + EPS_);
;         const int row = row0 + r;
; #pragma unroll
;         for (int hf = 0; hf < 2; ++hf) { const int c = hf * 512 + lane * 8;
;             float y[8], x8[8];
; #pragma unroll
;             for (int j = 0; j < 4; ++j) { y[j] = v[r][hf * 8 + j] * rs * g0[hf][j]; y[4 + j] = v[r][hf * 8 + 4 + j] * rs * g1[hf][j]; }
; #pragma unroll
;             for (int j = 0; j < 8; ++j) x8[j] = v[r][hf * 8 + j];
;             if (cpy) *(u32x4*)(cpy + (size_t)row * 1024 + c) = pack8(x8);
;             if (outn) { *(f32x4*)(outn + (size_t)row * 1024 + c) = (f32x4){y[0], y[1], y[2], y[3]}; *(f32x4*)(outn + (size_t)row * 1024 + c + 4) = (f32x4){y[4], y[5], y[6], y[7]}; }
;             if (H) *(u32x4*)(H + (size_t)row * 1024 + c) = pack8(y); }
	v_add_f32_e32 v22, v22, v23
	s_nop 1
	v_mov_b32_dpp v23, v22 row_half_mirror row_mask:0xf bank_mask:0xf
	s_waitcnt lgkmcnt(0)
	v_add_f32_e32 v22, v22, v23
	s_nop 1
	v_mov_b32_dpp v23, v22 quad_perm:[2,3,0,1] row_mask:0xf bank_mask:0xf
	s_waitcnt lgkmcnt(0)
	v_add_f32_e32 v22, v22, v23
	s_nop 1
	v_mov_b32_dpp v23, v22 quad_perm:[1,0,3,2] row_mask:0xf bank_mask:0xf
	s_waitcnt lgkmcnt(0)
	v_add_f32_e32 v22, v22, v23
	v_fmamk_f32 v22, v22, 0x3a800000, v211
	v_cmp_gt_f32_e32 vcc, s33, v22
	v_mul_f32_e32 v23, 0x4b800000, v22
	s_nop 0
	v_cndmask_b32_e32 v22, v22, v23, vcc
	v_rsq_f32_e32 v22, v22
	s_nop 0
	v_mul_f32_e32 v23, 0x45800000, v22
	v_cndmask_b32_e32 v44, v22, v23, vcc
	v_mul_f32_e32 v23, v44, v74
	v_mul_f32_e32 v22, v44, v73
	v_mul_f32_e32 v24, v14, v23
	v_mul_f32_e32 v23, v44, v71
	v_mul_f32_e32 v25, v44, v72
	v_mul_f32_e32 v30, v44, v69
	v_mul_f32_e32 v31, v44, v70
	v_mul_f32_e32 v22, v18, v22
	v_mul_f32_e32 v23, v19, v23
	v_mul_f32_e32 v25, v15, v25
	v_mul_f32_e32 v30, v20, v30
	v_mul_f32_e32 v31, v16, v31
	v_mul_f32_e32 v45, v44, v67
	v_mul_f32_e32 v46, v44, v68
	v_mul_f32_e32 v45, v21, v45
	v_mul_f32_e32 v46, v17, v46
	v_cvt_pk_bf16_f32 v22, v22, v23
	v_cvt_pk_bf16_f32 v23, v30, v45
	v_cvt_pk_bf16_f32 v24, v24, v25
	v_cvt_pk_bf16_f32 v25, v31, v46
	v_lshl_add_u64 v[30:31], v[36:37], 0, v[42:43]
	global_store_dwordx4 v[30:31], v[22:25], off
	v_mul_f32_e32 v3, v44, v3
	v_mul_f32_e32 v2, v44, v2
	v_mul_f32_e32 v22, v44, v66
	v_mul_f32_e32 v23, v44, v65
	v_mul_f32_e32 v24, v44, v64
	v_mul_f32_e32 v22, v10, v22
	v_mul_f32_e32 v23, v11, v23
	v_mul_f32_e32 v24, v12, v24
	v_mul_f32_e32 v25, v44, v27
	v_mul_f32_e32 v27, v44, v63
	v_mul_f32_e32 v3, v6, v3
	v_mul_f32_e32 v2, v7, v2
	v_mul_f32_e32 v25, v8, v25
	v_mul_f32_e32 v27, v13, v27
	v_mul_f32_e32 v26, v44, v26
	v_cvt_pk_bf16_f32 v22, v22, v23
	v_cvt_pk_bf16_f32 v23, v24, v27
	v_cvt_pk_bf16_f32 v24, v3, v2
	v_mul_f32_e32 v26, v9, v26
	v_cvt_pk_bf16_f32 v25, v25, v26
	global_store_dwordx4 v[30:31], v[22:25], off offset:1024
	s_nop 1
	v_mul_f32_e32 v24, v61, v61
	v_fmac_f32_e32 v24, v59, v59
	v_fmac_f32_e32 v24, v57, v57
	v_fmac_f32_e32 v24, v55, v55
	v_fmac_f32_e32 v24, v62, v62
	v_fmac_f32_e32 v24, v60, v60
	v_fmac_f32_e32 v24, v58, v58
	v_fmac_f32_e32 v24, v56, v56
	v_fmac_f32_e32 v24, v39, v39
	v_fmac_f32_e32 v24, v29, v29
	v_fmac_f32_e32 v24, v28, v28
	v_and_b32_e32 v22, 0xffff0000, v4
	v_lshlrev_b32_e32 v23, 16, v4
	v_fmac_f32_e32 v24, v0, v0
	v_pk_mul_f32 v[2:3], v[22:23], v[22:23]
	v_lshlrev_b32_e32 v25, 16, v5
	v_add_f32_e32 v3, v3, v24
	v_and_b32_e32 v24, 0xffff0000, v5
	v_add_f32_e32 v4, v2, v3
	v_pk_mul_f32 v[2:3], v[24:25], v[24:25]
	s_nop 0
	v_add_f32_e32 v3, v3, v4
	v_add_f32_e32 v2, v2, v3
	ds_bpermute_b32 v3, v49, v2
	s_waitcnt lgkmcnt(0)
	v_add_f32_e32 v2, v2, v3
	ds_bpermute_b32 v3, v50, v2
	s_waitcnt lgkmcnt(0)
	v_add_f32_e32 v2, v2, v3
	s_nop 1
	v_mov_b32_dpp v3, v2 row_mirror row_mask:0xf bank_mask:0xf
	s_waitcnt lgkmcnt(0)
	v_add_f32_e32 v2, v2, v3
	s_nop 1
	v_mov_b32_dpp v3, v2 row_half_mirror row_mask:0xf bank_mask:0xf
	s_waitcnt lgkmcnt(0)
	v_add_f32_e32 v2, v2, v3
	s_nop 1
	v_mov_b32_dpp v3, v2 quad_perm:[2,3,0,1] row_mask:0xf bank_mask:0xf
	s_waitcnt lgkmcnt(0)
	v_add_f32_e32 v2, v2, v3
	s_nop 1
	v_mov_b32_dpp v3, v2 quad_perm:[1,0,3,2] row_mask:0xf bank_mask:0xf
	s_waitcnt lgkmcnt(0)
	v_add_f32_e32 v2, v2, v3
	v_fmamk_f32 v2, v2, 0x3a800000, v211
	v_cmp_gt_f32_e32 vcc, s33, v2
	v_mul_f32_e32 v3, 0x4b800000, v2
	s_nop 0
	v_cndmask_b32_e32 v2, v2, v3, vcc
	v_rsq_f32_e32 v2, v2
	s_nop 0
	v_mul_f32_e32 v3, 0x45800000, v2
	v_cndmask_b32_e32 v26, v2, v3, vcc
	v_mul_f32_e32 v3, v26, v62
	v_mul_f32_e32 v5, v26, v60
	v_mul_f32_e32 v2, v26, v61
	v_mul_f32_e32 v4, v14, v3
	v_mul_f32_e32 v3, v26, v59
	v_mul_f32_e32 v5, v15, v5
	v_mul_f32_e32 v14, v26, v57
	v_mul_f32_e32 v15, v26, v58
	v_mul_f32_e32 v2, v18, v2
	v_mul_f32_e32 v3, v19, v3
	v_mul_f32_e32 v14, v20, v14
	v_mul_f32_e32 v15, v16, v15
	v_mul_f32_e32 v16, v26, v55
	v_mul_f32_e32 v18, v26, v56
	v_mul_f32_e32 v16, v21, v16
	v_mul_f32_e32 v17, v17, v18
	v_cvt_pk_bf16_f32 v2, v2, v3
	v_cvt_pk_bf16_f32 v3, v14, v16
	v_cvt_pk_bf16_f32 v4, v4, v5
	v_cvt_pk_bf16_f32 v5, v15, v17
	v_lshl_add_u64 v[14:15], v[36:37], 0, v[40:41]
	global_store_dwordx4 v[14:15], v[2:5], off
	v_cmp_lt_i32_e32 vcc, s58, v48
	v_mul_f32_e32 v0, v26, v0
	v_mul_f32_e32 v3, v26, v23
	v_mul_f32_e32 v5, v26, v22
	v_mul_f32_e32 v2, v26, v39
	v_mul_f32_e32 v4, v6, v3
	v_mul_f32_e32 v3, v26, v29
	v_mul_f32_e32 v5, v7, v5
	v_mul_f32_e32 v7, v26, v25
	v_mul_f32_e32 v2, v10, v2
	v_mul_f32_e32 v3, v11, v3
	v_mul_f32_e32 v6, v26, v28
	v_mul_f32_e32 v7, v8, v7
	v_mul_f32_e32 v8, v26, v24
	s_or_b64 s[42:43], vcc, s[42:43]
	v_mul_f32_e32 v6, v12, v6
	v_mul_f32_e32 v0, v13, v0
	v_mul_f32_e32 v8, v9, v8
	v_cvt_pk_bf16_f32 v2, v2, v3
	v_cvt_pk_bf16_f32 v3, v6, v0
	v_cvt_pk_bf16_f32 v4, v4, v5
	v_cvt_pk_bf16_f32 v5, v7, v8
	global_store_dwordx4 v[14:15], v[2:5], off offset:1024
	s_waitcnt vmcnt(8)
	s_andn2_b64 exec, exec, s[42:43]
	s_cbranch_execnz .LBB0_52
